# group-scoped arrive/poll (32 workgroups of one batch-head) replaces the grid barrier between the HGRN scan and second pass; scan and layer-1 weight-copy stores write-through
# speedup vs baseline: 1.0025x; 1.0025x over previous
; #define LAS __attribute__((address_space(3)))
; __device__ __forceinline__ void transpose_item(const float* W, int K, int N, bf16* WT, int prow0, int k0, int n0, LAS float* scr, int lane) {
;     float tv[32];
; #pragma unroll
;     for (int i = 0; i < 32; ++i) { const int kk = 2 * i + (lane >> 5), c = n0 + (lane & 31); tv[i] = (c < N) ? W[(size_t)(k0 + kk) * N + c] : 0.f; }
; __device__ __forceinline__ void weight_copy_items(const Args& a, LAS unsigned char* lds, int lo, int hi, int G) {
;     ...
;     for (int it = lo + (int)blockIdx.x * NWAVES + wave; it < hi; it += G * NWAVES) {
;         int r = it;
;         if (r < I0) { const int kb = r / 96, nb = r % 96; transpose_item(a.in[6], D, N0, (bf16*)(ws + WS_W0IN), 32 * nb, 64 * kb, 32 * nb, scr, lane); continue; } r -= I0;
;         if (r < I4) { const int gi = r >> 3, kb = (r >> 2) & 1, nb = r & 3; transpose_item(a.in[8] + (size_t)gi * 128 * 128, 128, 128, (bf16*)(ws + WS_POOLW) + (size_t)gi * 128 * 128, 32 * nb, 64 * kb, 32 * nb, scr, lane); continue; } r -= I4;
;         if (r < I1) { const int kb = r / 32, nb = r % 32; transpose_item(a.in[10], D, D, (bf16*)(ws + WS_W0OUT), 32 * nb, 64 * kb, 32 * nb, scr, lane); continue; } r -= I1;
;         if (r < I2) { const int kb = r / 129, lg = r % 129; const int pg = lg < 128 ? (8 * (lg >> 3) + 4 * (lg & 1) + ((lg & 7) >> 1)) : 128;
;             transpose_item(a.in[11], D, N1L, (bf16*)(ws + WS_W1IN), 32 * pg, 64 * kb, 32 * lg, scr, lane); continue; } r -= I2;
;         { const int kb = r / 32, nb = r % 32; transpose_item(a.in[15], D, D, (bf16*)(ws + WS_W1OUT), 32 * nb, 64 * kb, 32 * nb, scr, lane); }
.LBB0_264:
	s_movk_i32 s5, 0x5ff
	v_cmp_lt_i32_e32 vcc, s5, v18
	s_and_saveexec_b64 s[14:15], vcc
	s_xor_b64 s[40:41], exec, s[14:15]
	s_cbranch_execz .LBB0_344
	s_movk_i32 s5, 0x61f
	v_cmp_lt_u32_e32 vcc, s5, v18
	s_and_saveexec_b64 s[14:15], vcc
	s_xor_b64 s[42:43], exec, s[14:15]
	s_cbranch_execz .LBB0_341
	s_movk_i32 s5, 0x81f
	v_cmp_lt_u32_e32 vcc, s5, v18
	s_and_saveexec_b64 s[14:15], vcc
	s_xor_b64 s[44:45], exec, s[14:15]
	s_cbranch_execz .LBB0_338
	s_movk_i32 s5, 0x102f
	v_cmp_lt_u32_e32 vcc, s5, v18
	s_and_saveexec_b64 s[14:15], vcc
	s_xor_b64 s[36:37], exec, s[14:15]
	s_cbranch_execz .LBB0_269
	v_and_b32_e32 v11, 0x3e0, v27
	v_add_u32_e32 v0, 0xffffdfa0, v28
	v_and_b32_e32 v37, 0x7fffffc0, v0
	v_or_b32_e32 v0, v11, v19
	v_or_b32_e32 v14, v37, v20
	v_lshlrev_b32_e32 v0, 2, v0
	v_lshl_add_u64 v[12:13], s[66:67], 0, v[0:1]
	v_or_b32_e32 v0, 2, v14
	v_lshlrev_b64 v[38:39], 12, v[0:1]
	v_or_b32_e32 v0, 4, v14
	v_lshlrev_b64 v[40:41], 12, v[0:1]
	v_or_b32_e32 v0, 6, v14
	v_lshlrev_b64 v[42:43], 12, v[0:1]
	v_or_b32_e32 v0, 8, v14
	v_lshlrev_b64 v[44:45], 12, v[0:1]
	v_or_b32_e32 v0, 10, v14
	v_mov_b32_e32 v15, v1
	v_lshlrev_b64 v[46:47], 12, v[0:1]
	v_or_b32_e32 v0, 12, v14
	v_lshlrev_b64 v[16:17], 12, v[14:15]
	v_lshlrev_b64 v[48:49], 12, v[0:1]
	v_or_b32_e32 v0, 14, v14
	v_lshl_add_u64 v[16:17], v[12:13], 0, v[16:17]
	v_lshlrev_b64 v[50:51], 12, v[0:1]
	v_or_b32_e32 v0, 16, v14
	v_lshl_add_u64 v[38:39], v[12:13], 0, v[38:39]
	v_lshl_add_u64 v[40:41], v[12:13], 0, v[40:41]
	v_lshl_add_u64 v[42:43], v[12:13], 0, v[42:43]
	v_lshl_add_u64 v[44:45], v[12:13], 0, v[44:45]
	v_lshl_add_u64 v[46:47], v[12:13], 0, v[46:47]
	v_lshl_add_u64 v[48:49], v[12:13], 0, v[48:49]
	v_lshl_add_u64 v[50:51], v[12:13], 0, v[50:51]
	global_load_dword v52, v[16:17], off
	global_load_dword v53, v[38:39], off
	global_load_dword v54, v[40:41], off
	global_load_dword v55, v[42:43], off
	global_load_dword v56, v[44:45], off
	global_load_dword v57, v[46:47], off
	global_load_dword v58, v[48:49], off
	global_load_dword v59, v[50:51], off
	v_lshlrev_b64 v[16:17], 12, v[0:1]
	v_or_b32_e32 v0, 18, v14
	v_lshlrev_b64 v[38:39], 12, v[0:1]
	v_or_b32_e32 v0, 20, v14
	v_lshlrev_b64 v[40:41], 12, v[0:1]
	v_or_b32_e32 v0, 22, v14
	v_lshlrev_b64 v[42:43], 12, v[0:1]
	v_or_b32_e32 v0, 24, v14
	v_lshlrev_b64 v[44:45], 12, v[0:1]
	v_or_b32_e32 v0, 26, v14
	v_lshlrev_b64 v[46:47], 12, v[0:1]
	v_or_b32_e32 v0, 28, v14
	v_lshlrev_b64 v[48:49], 12, v[0:1]
	v_or_b32_e32 v0, 30, v14
	v_lshl_add_u64 v[16:17], v[12:13], 0, v[16:17]
	v_lshlrev_b64 v[50:51], 12, v[0:1]
	v_or_b32_e32 v0, 32, v14
	v_lshl_add_u64 v[38:39], v[12:13], 0, v[38:39]
	v_lshl_add_u64 v[40:41], v[12:13], 0, v[40:41]
	v_lshl_add_u64 v[42:43], v[12:13], 0, v[42:43]
	v_lshl_add_u64 v[44:45], v[12:13], 0, v[44:45]
	v_lshl_add_u64 v[46:47], v[12:13], 0, v[46:47]
	v_lshl_add_u64 v[48:49], v[12:13], 0, v[48:49]
	v_lshl_add_u64 v[50:51], v[12:13], 0, v[50:51]
	global_load_dword v60, v[16:17], off
	global_load_dword v61, v[38:39], off
	global_load_dword v62, v[40:41], off
	global_load_dword v63, v[42:43], off
	global_load_dword v64, v[44:45], off
	global_load_dword v65, v[46:47], off
	global_load_dword v66, v[48:49], off
	global_load_dword v67, v[50:51], off
	v_lshlrev_b64 v[16:17], 12, v[0:1]
	v_or_b32_e32 v0, 34, v14
	v_lshlrev_b64 v[38:39], 12, v[0:1]
	v_or_b32_e32 v0, 36, v14
	v_lshlrev_b64 v[40:41], 12, v[0:1]
	v_or_b32_e32 v0, 38, v14
	v_lshlrev_b64 v[42:43], 12, v[0:1]
	v_or_b32_e32 v0, 40, v14
	v_lshlrev_b64 v[44:45], 12, v[0:1]
	v_or_b32_e32 v0, 42, v14
	v_lshlrev_b64 v[46:47], 12, v[0:1]
	v_or_b32_e32 v0, 44, v14
	v_lshlrev_b64 v[48:49], 12, v[0:1]
	v_or_b32_e32 v0, 46, v14
	v_lshlrev_b64 v[50:51], 12, v[0:1]
	v_lshl_add_u64 v[16:17], v[12:13], 0, v[16:17]
	v_lshl_add_u64 v[50:51], v[12:13], 0, v[50:51]
	v_or_b32_e32 v0, 48, v14
	v_lshl_add_u64 v[38:39], v[12:13], 0, v[38:39]
	v_lshl_add_u64 v[40:41], v[12:13], 0, v[40:41]
	v_lshl_add_u64 v[42:43], v[12:13], 0, v[42:43]
	v_lshl_add_u64 v[44:45], v[12:13], 0, v[44:45]
	v_lshl_add_u64 v[46:47], v[12:13], 0, v[46:47]
	v_lshl_add_u64 v[48:49], v[12:13], 0, v[48:49]
	global_load_dword v68, v[16:17], off
	global_load_dword v69, v[38:39], off
	global_load_dword v70, v[40:41], off
	global_load_dword v71, v[42:43], off
	global_load_dword v72, v[44:45], off
	global_load_dword v73, v[46:47], off
	global_load_dword v74, v[48:49], off
	s_nop 0
	global_load_dword v50, v[50:51], off
	v_lshlrev_b64 v[16:17], 12, v[0:1]
	v_or_b32_e32 v0, 50, v14
	v_lshlrev_b64 v[38:39], 12, v[0:1]
	v_or_b32_e32 v0, 52, v14
	v_lshlrev_b64 v[40:41], 12, v[0:1]
	v_or_b32_e32 v0, 54, v14
	v_lshlrev_b64 v[42:43], 12, v[0:1]
	v_or_b32_e32 v0, 56, v14
	v_lshlrev_b64 v[44:45], 12, v[0:1]
	v_or_b32_e32 v0, 58, v14
	v_lshlrev_b64 v[46:47], 12, v[0:1]
	v_or_b32_e32 v0, 60, v14
	v_lshlrev_b64 v[48:49], 12, v[0:1]
	v_or_b32_e32 v0, 62, v14
	v_lshlrev_b64 v[14:15], 12, v[0:1]
	v_lshl_add_u64 v[16:17], v[12:13], 0, v[16:17]
	v_lshl_add_u64 v[38:39], v[12:13], 0, v[38:39]
	v_lshl_add_u64 v[40:41], v[12:13], 0, v[40:41]
	v_lshl_add_u64 v[42:43], v[12:13], 0, v[42:43]
	v_lshl_add_u64 v[44:45], v[12:13], 0, v[44:45]
	v_lshl_add_u64 v[46:47], v[12:13], 0, v[46:47]
	v_lshl_add_u64 v[48:49], v[12:13], 0, v[48:49]
	v_lshl_add_u64 v[12:13], v[12:13], 0, v[14:15]
	global_load_dword v0, v[16:17], off
	global_load_dword v14, v[38:39], off
	global_load_dword v15, v[40:41], off
	s_nop 0
	global_load_dword v16, v[42:43], off
	global_load_dword v17, v[44:45], off
	global_load_dword v38, v[46:47], off
	global_load_dword v39, v[48:49], off
	s_nop 0
	global_load_dword v12, v[12:13], off
	s_waitcnt vmcnt(30)
; #define LAS __attribute__((address_space(3)))
; __device__ __forceinline__ unsigned pk2(float lo, float hi) { f32x2_t v = {lo, hi}; bf16x2_t b = __builtin_convertvector(v, bf16x2_t); return __builtin_bit_cast(unsigned, b); }
; __device__ __forceinline__ void transpose_item(const float* W, int K, int N, bf16* WT, int prow0, int k0, int n0, LAS float* scr, int lane) {
;     ...
;     for (int i = 0; i < 32; ++i) { const int kk = 2 * i + (lane >> 5); scr[kk * 33 + (lane & 31)] = tv[i]; }
;     asm volatile("s_waitcnt lgkmcnt(0)" ::: "memory");
;     const int c = lane & 7;
; #pragma unroll
;     for (int j = 0; j < 4; ++j) { const int n = (lane >> 3) + 8 * j; const LAS float* s = scr + (8 * c) * 33 + n;
;         v4u o; o.x = pk2(s[0 * 33], s[1 * 33]); o.y = pk2(s[2 * 33], s[3 * 33]); o.z = pk2(s[4 * 33], s[5 * 33]); o.w = pk2(s[6 * 33], s[7 * 33]);
;         *(v4u*)(WT + (size_t)(prow0 + n) * K + k0 + 8 * c) = o; }
;     asm volatile("s_waitcnt lgkmcnt(0)" ::: "memory");
	ds_write2_b32 v21, v52, v53 offset1:66
	s_waitcnt vmcnt(28)
	ds_write2_b32 v21, v54, v55 offset0:132 offset1:198
	s_waitcnt vmcnt(26)
	ds_write2_b32 v30, v56, v57 offset0:8 offset1:74
	s_waitcnt vmcnt(24)
	ds_write2_b32 v30, v58, v59 offset0:140 offset1:206
	s_waitcnt vmcnt(22)
	ds_write2_b32 v31, v60, v61 offset0:16 offset1:82
	s_waitcnt vmcnt(20)
	ds_write2_b32 v31, v62, v63 offset0:148 offset1:214
	s_waitcnt vmcnt(18)
	ds_write2_b32 v32, v64, v65 offset0:24 offset1:90
	s_waitcnt vmcnt(16)
	ds_write2_b32 v32, v66, v67 offset0:156 offset1:222
	s_waitcnt vmcnt(14)
	ds_write2_b32 v33, v68, v69 offset0:32 offset1:98
	s_waitcnt vmcnt(12)
	ds_write2_b32 v33, v70, v71 offset0:164 offset1:230
	s_waitcnt vmcnt(10)
	ds_write2_b32 v34, v72, v73 offset0:40 offset1:106
	s_waitcnt vmcnt(8)
	ds_write2_b32 v34, v74, v50 offset0:172 offset1:238
	s_waitcnt vmcnt(6)
	ds_write2_b32 v35, v0, v14 offset0:48 offset1:114
	s_waitcnt vmcnt(4)
	ds_write2_b32 v35, v15, v16 offset0:180 offset1:246
	s_waitcnt vmcnt(2)
	ds_write2_b32 v36, v17, v38 offset0:56 offset1:122
	s_waitcnt vmcnt(0)
	ds_write2_b32 v36, v39, v12 offset0:188 offset1:254
	s_waitcnt lgkmcnt(0)
	ds_read2_b32 v[16:17], v23 offset0:33 offset1:41
	ds_read2_b32 v[38:39], v23 offset1:8
	ds_read2_b32 v[40:41], v23 offset0:66 offset1:74
	ds_read2_b32 v[42:43], v23 offset0:99 offset1:107
	ds_read2_b32 v[44:45], v23 offset0:132 offset1:140
	ds_read2_b32 v[46:47], v23 offset0:165 offset1:173
	ds_read2_b32 v[48:49], v23 offset0:198 offset1:206
	ds_read2_b32 v[50:51], v23 offset0:231 offset1:239
	v_lshlrev_b32_e32 v0, 1, v37
	v_lshl_add_u64 v[52:53], v[2:3], 0, v[0:1]
	v_or_b32_e32 v0, v11, v22
	v_lshlrev_b32_e32 v0, 11, v0
	s_waitcnt lgkmcnt(6)
	v_cvt_pk_bf16_f32 v12, v38, v16
	s_waitcnt lgkmcnt(4)
	v_cvt_pk_bf16_f32 v13, v40, v42
	s_waitcnt lgkmcnt(2)
	v_cvt_pk_bf16_f32 v14, v44, v46
	s_waitcnt lgkmcnt(0)
	v_cvt_pk_bf16_f32 v15, v48, v50
	v_lshl_add_u64 v[54:55], v[52:53], 0, v[0:1]
	global_store_dwordx4 v[54:55], v[12:15], off sc1
	v_or_b32_e32 v0, v11, v24
	v_lshlrev_b32_e32 v0, 11, v0
	v_cvt_pk_bf16_f32 v12, v39, v17
	v_cvt_pk_bf16_f32 v13, v41, v43
	v_cvt_pk_bf16_f32 v14, v45, v47
	v_cvt_pk_bf16_f32 v15, v49, v51
	ds_read2_b32 v[38:39], v23 offset0:49 offset1:57
	ds_read2_b32 v[40:41], v23 offset0:16 offset1:24
	ds_read2_b32 v[42:43], v23 offset0:82 offset1:90
	ds_read2_b32 v[44:45], v23 offset0:115 offset1:123
	ds_read2_b32 v[46:47], v23 offset0:148 offset1:156
	ds_read2_b32 v[48:49], v23 offset0:181 offset1:189
	ds_read2_b32 v[50:51], v23 offset0:214 offset1:222
	ds_read2_b32 v[54:55], v23 offset0:247 offset1:255
	v_lshl_add_u64 v[16:17], v[52:53], 0, v[0:1]
	v_or_b32_e32 v0, v11, v25
	v_lshlrev_b32_e32 v0, 11, v0
	global_store_dwordx4 v[16:17], v[12:15], off sc1
	v_lshl_add_u64 v[16:17], v[52:53], 0, v[0:1]
	v_or_b32_e32 v0, v11, v26
	s_waitcnt lgkmcnt(6)
	v_cvt_pk_bf16_f32 v12, v40, v38
	s_waitcnt lgkmcnt(4)
	v_cvt_pk_bf16_f32 v13, v42, v44
	s_waitcnt lgkmcnt(2)
	v_cvt_pk_bf16_f32 v14, v46, v48
	s_waitcnt lgkmcnt(0)
	v_cvt_pk_bf16_f32 v15, v50, v54
	v_lshlrev_b32_e32 v0, 11, v0
	global_store_dwordx4 v[16:17], v[12:15], off sc1
	v_lshl_add_u64 v[16:17], v[52:53], 0, v[0:1]
	s_nop 0
	v_cvt_pk_bf16_f32 v12, v41, v39
	v_cvt_pk_bf16_f32 v13, v43, v45
	v_cvt_pk_bf16_f32 v14, v47, v49
	v_cvt_pk_bf16_f32 v15, v51, v55
	global_store_dwordx4 v[16:17], v[12:15], off sc1
	s_waitcnt lgkmcnt(0)

; #define LAS __attribute__((address_space(3)))
; __device__ __forceinline__ unsigned pk2(float lo, float hi) { f32x2_t v = {lo, hi}; bf16x2_t b = __builtin_convertvector(v, bf16x2_t); return __builtin_bit_cast(unsigned, b); }
; __device__ __forceinline__ void transpose_item(const float* W, int K, int N, bf16* WT, int prow0, int k0, int n0, LAS float* scr, int lane) {
;     ...
;     for (int i = 0; i < 32; ++i) { const int kk = 2 * i + (lane >> 5); scr[kk * 33 + (lane & 31)] = tv[i]; }
;     asm volatile("s_waitcnt lgkmcnt(0)" ::: "memory");
;     const int c = lane & 7;
; #pragma unroll
;     for (int j = 0; j < 4; ++j) { const int n = (lane >> 3) + 8 * j; const LAS float* s = scr + (8 * c) * 33 + n;
;         v4u o; o.x = pk2(s[0 * 33], s[1 * 33]); o.y = pk2(s[2 * 33], s[3 * 33]); o.z = pk2(s[4 * 33], s[5 * 33]); o.w = pk2(s[6 * 33], s[7 * 33]);
;         *(v4u*)(WT + (size_t)(prow0 + n) * K + k0 + 8 * c) = o; }
;     asm volatile("s_waitcnt lgkmcnt(0)" ::: "memory");
.LBB0_336:
	s_or_b64 exec, exec, s[18:19]
	s_waitcnt vmcnt(0)
	ds_write2_b32 v21, v15, v16 offset1:66
	ds_write2_b32 v21, v37, v17 offset0:132 offset1:198
	ds_write2_b32 v30, v39, v38 offset0:8 offset1:74
	ds_write2_b32 v30, v41, v40 offset0:140 offset1:206
	ds_write2_b32 v31, v43, v42 offset0:16 offset1:82
	ds_write2_b32 v31, v45, v44 offset0:148 offset1:214
	ds_write2_b32 v32, v47, v46 offset0:24 offset1:90
	ds_write2_b32 v32, v49, v48 offset0:156 offset1:222
	ds_write2_b32 v33, v51, v50 offset0:32 offset1:98
	ds_write2_b32 v33, v53, v52 offset0:164 offset1:230
	ds_write2_b32 v34, v55, v54 offset0:40 offset1:106
	ds_write2_b32 v34, v57, v56 offset0:172 offset1:238
	ds_write2_b32 v35, v59, v58 offset0:48 offset1:114
	ds_write2_b32 v35, v61, v60 offset0:180 offset1:246
	ds_write2_b32 v36, v63, v62 offset0:56 offset1:122
	ds_write2_b32 v36, v65, v64 offset0:188 offset1:254
	s_waitcnt lgkmcnt(0)
	ds_read2_b32 v[16:17], v23 offset0:33 offset1:41
	ds_read2_b32 v[38:39], v23 offset1:8
	ds_read2_b32 v[40:41], v23 offset0:66 offset1:74
	ds_read2_b32 v[42:43], v23 offset0:99 offset1:107
	ds_read2_b32 v[44:45], v23 offset0:132 offset1:140
	ds_read2_b32 v[46:47], v23 offset0:165 offset1:173
	ds_read2_b32 v[48:49], v23 offset0:198 offset1:206
	ds_read2_b32 v[50:51], v23 offset0:231 offset1:239
	v_lshlrev_b32_e32 v0, 1, v14
	v_lshl_add_u64 v[52:53], v[4:5], 0, v[0:1]
	v_or_b32_e32 v0, v11, v22
	v_lshlrev_b32_e32 v0, 11, v0
	s_waitcnt lgkmcnt(6)
	v_cvt_pk_bf16_f32 v12, v38, v16
	s_waitcnt lgkmcnt(4)
	v_cvt_pk_bf16_f32 v13, v40, v42
	s_waitcnt lgkmcnt(2)
	v_cvt_pk_bf16_f32 v14, v44, v46
	s_waitcnt lgkmcnt(0)
	v_cvt_pk_bf16_f32 v15, v48, v50
	v_lshl_add_u64 v[54:55], v[52:53], 0, v[0:1]
	global_store_dwordx4 v[54:55], v[12:15], off sc1
	v_or_b32_e32 v0, v11, v24
	v_lshlrev_b32_e32 v0, 11, v0
	v_cvt_pk_bf16_f32 v12, v39, v17
	v_cvt_pk_bf16_f32 v13, v41, v43
	v_cvt_pk_bf16_f32 v14, v45, v47
	v_cvt_pk_bf16_f32 v15, v49, v51
	ds_read2_b32 v[38:39], v23 offset0:49 offset1:57
	ds_read2_b32 v[40:41], v23 offset0:16 offset1:24
	ds_read2_b32 v[42:43], v23 offset0:82 offset1:90
	ds_read2_b32 v[44:45], v23 offset0:115 offset1:123
	ds_read2_b32 v[46:47], v23 offset0:148 offset1:156
	ds_read2_b32 v[48:49], v23 offset0:181 offset1:189
	ds_read2_b32 v[50:51], v23 offset0:214 offset1:222
	ds_read2_b32 v[54:55], v23 offset0:247 offset1:255
	v_lshl_add_u64 v[16:17], v[52:53], 0, v[0:1]
	v_or_b32_e32 v0, v11, v25
	v_lshlrev_b32_e32 v0, 11, v0
	global_store_dwordx4 v[16:17], v[12:15], off sc1
	v_lshl_add_u64 v[16:17], v[52:53], 0, v[0:1]
	v_or_b32_e32 v0, v11, v26
	s_waitcnt lgkmcnt(6)
	v_cvt_pk_bf16_f32 v12, v40, v38
	s_waitcnt lgkmcnt(4)
	v_cvt_pk_bf16_f32 v13, v42, v44
	s_waitcnt lgkmcnt(2)
	v_cvt_pk_bf16_f32 v14, v46, v48
	s_waitcnt lgkmcnt(0)
	v_cvt_pk_bf16_f32 v15, v50, v54
	v_lshlrev_b32_e32 v0, 11, v0
	global_store_dwordx4 v[16:17], v[12:15], off sc1
	v_lshl_add_u64 v[16:17], v[52:53], 0, v[0:1]
	s_nop 0
	v_cvt_pk_bf16_f32 v12, v41, v39
	v_cvt_pk_bf16_f32 v13, v43, v45
	v_cvt_pk_bf16_f32 v14, v47, v49
	v_cvt_pk_bf16_f32 v15, v51, v55
	global_store_dwordx4 v[16:17], v[12:15], off sc1
	s_waitcnt lgkmcnt(0)

; #define LAS __attribute__((address_space(3)))
; __device__ __forceinline__ void transpose_item(const float* W, int K, int N, bf16* WT, int prow0, int k0, int n0, LAS float* scr, int lane) {
;     float tv[32];
; #pragma unroll
;     for (int i = 0; i < 32; ++i) { const int kk = 2 * i + (lane >> 5), c = n0 + (lane & 31); tv[i] = (c < N) ? W[(size_t)(k0 + kk) * N + c] : 0.f; }
; __device__ __forceinline__ void weight_copy_items(const Args& a, LAS unsigned char* lds, int lo, int hi, int G) {
;     ...
;         if (r < I1) { const int kb = r / 32, nb = r % 32; transpose_item(a.in[10], D, D, (bf16*)(ws + WS_W0OUT), 32 * nb, 64 * kb, 32 * nb, scr, lane); continue; } r -= I1;
.LBB0_338:
	s_andn2_saveexec_b64 s[36:37], s[44:45]
	s_cbranch_execz .LBB0_340
	v_add_u32_e32 v0, 0x20600, v27
	v_and_b32_e32 v11, 0x3e0, v0
	v_and_b32_e32 v0, 0x1fc0, v28
	v_add_u32_e32 v12, 0xfffff3c0, v0
	v_or_b32_e32 v0, v11, v19
	v_or_b32_e32 v16, v12, v20
	v_lshlrev_b32_e32 v0, 2, v0
	v_lshl_add_u64 v[14:15], s[56:57], 0, v[0:1]
	v_or_b32_e32 v0, 2, v16
	v_lshlrev_b64 v[40:41], 12, v[0:1]
	v_or_b32_e32 v0, 4, v16
	v_lshlrev_b64 v[42:43], 12, v[0:1]
	v_or_b32_e32 v0, 6, v16
	v_lshlrev_b64 v[44:45], 12, v[0:1]
	v_or_b32_e32 v0, 8, v16
	v_lshlrev_b64 v[46:47], 12, v[0:1]
	v_or_b32_e32 v0, 10, v16
	v_mov_b32_e32 v17, v1
	v_lshlrev_b64 v[48:49], 12, v[0:1]
	v_or_b32_e32 v0, 12, v16
	v_lshlrev_b64 v[38:39], 12, v[16:17]
	v_lshlrev_b64 v[50:51], 12, v[0:1]
	v_or_b32_e32 v0, 14, v16
	v_lshl_add_u64 v[38:39], v[14:15], 0, v[38:39]
	v_lshlrev_b64 v[52:53], 12, v[0:1]
	v_or_b32_e32 v0, 16, v16
	v_lshl_add_u64 v[40:41], v[14:15], 0, v[40:41]
	v_lshl_add_u64 v[42:43], v[14:15], 0, v[42:43]
	v_lshl_add_u64 v[44:45], v[14:15], 0, v[44:45]
	v_lshl_add_u64 v[46:47], v[14:15], 0, v[46:47]
	v_lshl_add_u64 v[48:49], v[14:15], 0, v[48:49]
	v_lshl_add_u64 v[50:51], v[14:15], 0, v[50:51]
	v_lshl_add_u64 v[52:53], v[14:15], 0, v[52:53]
	global_load_dword v13, v[38:39], off
	global_load_dword v37, v[40:41], off
	global_load_dword v54, v[42:43], off
	global_load_dword v55, v[44:45], off
	global_load_dword v56, v[46:47], off
	global_load_dword v57, v[48:49], off
	global_load_dword v58, v[50:51], off
	global_load_dword v59, v[52:53], off
	v_lshlrev_b64 v[38:39], 12, v[0:1]
	v_or_b32_e32 v0, 18, v16
	v_lshlrev_b64 v[40:41], 12, v[0:1]
	v_or_b32_e32 v0, 20, v16
	v_lshlrev_b64 v[42:43], 12, v[0:1]
	v_or_b32_e32 v0, 22, v16
	v_lshlrev_b64 v[44:45], 12, v[0:1]
	v_or_b32_e32 v0, 24, v16
	v_lshlrev_b64 v[46:47], 12, v[0:1]
	v_or_b32_e32 v0, 26, v16
	v_lshlrev_b64 v[48:49], 12, v[0:1]
	v_or_b32_e32 v0, 28, v16
	v_lshlrev_b64 v[50:51], 12, v[0:1]
	v_or_b32_e32 v0, 30, v16
	v_lshl_add_u64 v[38:39], v[14:15], 0, v[38:39]
	v_lshlrev_b64 v[52:53], 12, v[0:1]
	v_or_b32_e32 v0, 32, v16
	v_lshl_add_u64 v[40:41], v[14:15], 0, v[40:41]
	v_lshl_add_u64 v[42:43], v[14:15], 0, v[42:43]
	v_lshl_add_u64 v[44:45], v[14:15], 0, v[44:45]
	v_lshl_add_u64 v[46:47], v[14:15], 0, v[46:47]
	v_lshl_add_u64 v[48:49], v[14:15], 0, v[48:49]
	v_lshl_add_u64 v[50:51], v[14:15], 0, v[50:51]
	v_lshl_add_u64 v[52:53], v[14:15], 0, v[52:53]
	global_load_dword v60, v[38:39], off
	global_load_dword v61, v[40:41], off
	global_load_dword v62, v[42:43], off
	global_load_dword v63, v[44:45], off
	global_load_dword v64, v[46:47], off
	global_load_dword v65, v[48:49], off
	global_load_dword v66, v[50:51], off
	global_load_dword v67, v[52:53], off
	v_lshlrev_b64 v[38:39], 12, v[0:1]
	v_or_b32_e32 v0, 34, v16
	v_lshlrev_b64 v[40:41], 12, v[0:1]
	v_or_b32_e32 v0, 36, v16
	v_lshlrev_b64 v[42:43], 12, v[0:1]
	v_or_b32_e32 v0, 38, v16
	v_lshlrev_b64 v[44:45], 12, v[0:1]
	v_or_b32_e32 v0, 40, v16
	v_lshlrev_b64 v[46:47], 12, v[0:1]
	v_or_b32_e32 v0, 42, v16
	v_lshlrev_b64 v[48:49], 12, v[0:1]
	v_or_b32_e32 v0, 44, v16
	v_lshlrev_b64 v[50:51], 12, v[0:1]
	v_or_b32_e32 v0, 46, v16
	v_lshlrev_b64 v[52:53], 12, v[0:1]
	v_lshl_add_u64 v[38:39], v[14:15], 0, v[38:39]
	v_lshl_add_u64 v[52:53], v[14:15], 0, v[52:53]
	v_or_b32_e32 v0, 48, v16
	v_lshl_add_u64 v[40:41], v[14:15], 0, v[40:41]
	v_lshl_add_u64 v[42:43], v[14:15], 0, v[42:43]
	v_lshl_add_u64 v[44:45], v[14:15], 0, v[44:45]
	v_lshl_add_u64 v[46:47], v[14:15], 0, v[46:47]
	v_lshl_add_u64 v[48:49], v[14:15], 0, v[48:49]
	v_lshl_add_u64 v[50:51], v[14:15], 0, v[50:51]
	global_load_dword v68, v[38:39], off
	global_load_dword v69, v[40:41], off
	global_load_dword v70, v[42:43], off
	global_load_dword v71, v[44:45], off
	global_load_dword v72, v[46:47], off
	global_load_dword v73, v[48:49], off
	global_load_dword v74, v[50:51], off
	s_nop 0
	global_load_dword v52, v[52:53], off
	v_lshlrev_b64 v[38:39], 12, v[0:1]
	v_or_b32_e32 v0, 50, v16
	v_lshlrev_b64 v[40:41], 12, v[0:1]
	v_or_b32_e32 v0, 52, v16
	v_lshlrev_b64 v[42:43], 12, v[0:1]
	v_or_b32_e32 v0, 54, v16
	v_lshlrev_b64 v[44:45], 12, v[0:1]
	v_or_b32_e32 v0, 56, v16
	v_lshlrev_b64 v[46:47], 12, v[0:1]
	v_or_b32_e32 v0, 58, v16
	v_lshlrev_b64 v[48:49], 12, v[0:1]
	v_or_b32_e32 v0, 60, v16
	v_lshlrev_b64 v[50:51], 12, v[0:1]
	v_or_b32_e32 v0, 62, v16
	v_lshlrev_b64 v[16:17], 12, v[0:1]
	v_lshl_add_u64 v[38:39], v[14:15], 0, v[38:39]
	v_lshl_add_u64 v[40:41], v[14:15], 0, v[40:41]
	v_lshl_add_u64 v[42:43], v[14:15], 0, v[42:43]
	v_lshl_add_u64 v[44:45], v[14:15], 0, v[44:45]
	v_lshl_add_u64 v[46:47], v[14:15], 0, v[46:47]
	v_lshl_add_u64 v[48:49], v[14:15], 0, v[48:49]
	v_lshl_add_u64 v[50:51], v[14:15], 0, v[50:51]
	v_lshl_add_u64 v[14:15], v[14:15], 0, v[16:17]
	global_load_dword v0, v[38:39], off
	global_load_dword v16, v[40:41], off
	global_load_dword v17, v[42:43], off
	s_nop 0
	global_load_dword v38, v[44:45], off
	global_load_dword v39, v[46:47], off
	global_load_dword v40, v[48:49], off
	global_load_dword v41, v[50:51], off
	s_nop 0
	global_load_dword v14, v[14:15], off
	s_waitcnt vmcnt(30)
; #define LAS __attribute__((address_space(3)))
; __device__ __forceinline__ unsigned pk2(float lo, float hi) { f32x2_t v = {lo, hi}; bf16x2_t b = __builtin_convertvector(v, bf16x2_t); return __builtin_bit_cast(unsigned, b); }
; __device__ __forceinline__ void transpose_item(const float* W, int K, int N, bf16* WT, int prow0, int k0, int n0, LAS float* scr, int lane) {
;     ...
;     for (int i = 0; i < 32; ++i) { const int kk = 2 * i + (lane >> 5); scr[kk * 33 + (lane & 31)] = tv[i]; }
;     asm volatile("s_waitcnt lgkmcnt(0)" ::: "memory");
;     const int c = lane & 7;
; #pragma unroll
;     for (int j = 0; j < 4; ++j) { const int n = (lane >> 3) + 8 * j; const LAS float* s = scr + (8 * c) * 33 + n;
;         v4u o; o.x = pk2(s[0 * 33], s[1 * 33]); o.y = pk2(s[2 * 33], s[3 * 33]); o.z = pk2(s[4 * 33], s[5 * 33]); o.w = pk2(s[6 * 33], s[7 * 33]);
;         *(v4u*)(WT + (size_t)(prow0 + n) * K + k0 + 8 * c) = o; }
;     asm volatile("s_waitcnt lgkmcnt(0)" ::: "memory");
	ds_write2_b32 v21, v13, v37 offset1:66
	s_waitcnt vmcnt(28)
	ds_write2_b32 v21, v54, v55 offset0:132 offset1:198
	s_waitcnt vmcnt(26)
	ds_write2_b32 v30, v56, v57 offset0:8 offset1:74
	s_waitcnt vmcnt(24)
	ds_write2_b32 v30, v58, v59 offset0:140 offset1:206
	s_waitcnt vmcnt(22)
	ds_write2_b32 v31, v60, v61 offset0:16 offset1:82
	s_waitcnt vmcnt(20)
	ds_write2_b32 v31, v62, v63 offset0:148 offset1:214
	s_waitcnt vmcnt(18)
	ds_write2_b32 v32, v64, v65 offset0:24 offset1:90
	s_waitcnt vmcnt(16)
	ds_write2_b32 v32, v66, v67 offset0:156 offset1:222
	s_waitcnt vmcnt(14)
	ds_write2_b32 v33, v68, v69 offset0:32 offset1:98
	s_waitcnt vmcnt(12)
	ds_write2_b32 v33, v70, v71 offset0:164 offset1:230
	s_waitcnt vmcnt(10)
	ds_write2_b32 v34, v72, v73 offset0:40 offset1:106
	s_waitcnt vmcnt(8)
	ds_write2_b32 v34, v74, v52 offset0:172 offset1:238
	s_waitcnt vmcnt(6)
	ds_write2_b32 v35, v0, v16 offset0:48 offset1:114
	s_waitcnt vmcnt(4)
	ds_write2_b32 v35, v17, v38 offset0:180 offset1:246
	s_waitcnt vmcnt(2)
	ds_write2_b32 v36, v39, v40 offset0:56 offset1:122
	s_waitcnt vmcnt(0)
	ds_write2_b32 v36, v41, v14 offset0:188 offset1:254
	s_waitcnt lgkmcnt(0)
	ds_read2_b32 v[16:17], v23 offset0:33 offset1:41
	ds_read2_b32 v[38:39], v23 offset1:8
	ds_read2_b32 v[40:41], v23 offset0:66 offset1:74
	ds_read2_b32 v[42:43], v23 offset0:99 offset1:107
	ds_read2_b32 v[44:45], v23 offset0:132 offset1:140
	ds_read2_b32 v[46:47], v23 offset0:165 offset1:173
	ds_read2_b32 v[48:49], v23 offset0:198 offset1:206
	ds_read2_b32 v[50:51], v23 offset0:231 offset1:239
	v_mov_b32_e32 v13, v1
	v_or_b32_e32 v0, v11, v22
	v_lshl_add_u64 v[52:53], v[12:13], 1, v[6:7]
	v_lshlrev_b32_e32 v0, 11, v0
	s_waitcnt lgkmcnt(6)
	v_cvt_pk_bf16_f32 v12, v38, v16
	s_waitcnt lgkmcnt(4)
	v_cvt_pk_bf16_f32 v13, v40, v42
	s_waitcnt lgkmcnt(2)
	v_cvt_pk_bf16_f32 v14, v44, v46
	s_waitcnt lgkmcnt(0)
	v_cvt_pk_bf16_f32 v15, v48, v50
	v_lshl_add_u64 v[54:55], v[52:53], 0, v[0:1]
	global_store_dwordx4 v[54:55], v[12:15], off sc1
	v_or_b32_e32 v0, v11, v24
	v_lshlrev_b32_e32 v0, 11, v0
	v_cvt_pk_bf16_f32 v12, v39, v17
	v_cvt_pk_bf16_f32 v13, v41, v43
	v_cvt_pk_bf16_f32 v14, v45, v47
	v_cvt_pk_bf16_f32 v15, v49, v51
	ds_read2_b32 v[38:39], v23 offset0:49 offset1:57
	ds_read2_b32 v[40:41], v23 offset0:16 offset1:24
	ds_read2_b32 v[42:43], v23 offset0:82 offset1:90
	ds_read2_b32 v[44:45], v23 offset0:115 offset1:123
	ds_read2_b32 v[46:47], v23 offset0:148 offset1:156
	ds_read2_b32 v[48:49], v23 offset0:181 offset1:189
	ds_read2_b32 v[50:51], v23 offset0:214 offset1:222
	ds_read2_b32 v[54:55], v23 offset0:247 offset1:255
	v_lshl_add_u64 v[16:17], v[52:53], 0, v[0:1]
	v_or_b32_e32 v0, v11, v25
	v_lshlrev_b32_e32 v0, 11, v0
	global_store_dwordx4 v[16:17], v[12:15], off sc1
	v_lshl_add_u64 v[16:17], v[52:53], 0, v[0:1]
	v_or_b32_e32 v0, v11, v26
	s_waitcnt lgkmcnt(6)
	v_cvt_pk_bf16_f32 v12, v40, v38
	s_waitcnt lgkmcnt(4)
	v_cvt_pk_bf16_f32 v13, v42, v44
	s_waitcnt lgkmcnt(2)
	v_cvt_pk_bf16_f32 v14, v46, v48
	s_waitcnt lgkmcnt(0)
	v_cvt_pk_bf16_f32 v15, v50, v54
	v_lshlrev_b32_e32 v0, 11, v0
	global_store_dwordx4 v[16:17], v[12:15], off sc1
	v_lshl_add_u64 v[16:17], v[52:53], 0, v[0:1]
	s_nop 0
	v_cvt_pk_bf16_f32 v12, v41, v39
	v_cvt_pk_bf16_f32 v13, v43, v45
	v_cvt_pk_bf16_f32 v14, v47, v49
	v_cvt_pk_bf16_f32 v15, v51, v55
	global_store_dwordx4 v[16:17], v[12:15], off sc1
	s_waitcnt lgkmcnt(0)

; #define LAS __attribute__((address_space(3)))
; __device__ __forceinline__ unsigned pk2(float lo, float hi) { f32x2_t v = {lo, hi}; bf16x2_t b = __builtin_convertvector(v, bf16x2_t); return __builtin_bit_cast(unsigned, b); }
; __device__ __forceinline__ void transpose_item(const float* W, int K, int N, bf16* WT, int prow0, int k0, int n0, LAS float* scr, int lane) {
;     float tv[32];
; #pragma unroll
;     for (int i = 0; i < 32; ++i) { const int kk = 2 * i + (lane >> 5), c = n0 + (lane & 31); tv[i] = (c < N) ? W[(size_t)(k0 + kk) * N + c] : 0.f; }
; #pragma unroll
;     for (int i = 0; i < 32; ++i) { const int kk = 2 * i + (lane >> 5); scr[kk * 33 + (lane & 31)] = tv[i]; }
;     asm volatile("s_waitcnt lgkmcnt(0)" ::: "memory");
;     const int c = lane & 7;
; #pragma unroll
;     for (int j = 0; j < 4; ++j) { const int n = (lane >> 3) + 8 * j; const LAS float* s = scr + (8 * c) * 33 + n;
;         v4u o; o.x = pk2(s[0 * 33], s[1 * 33]); o.y = pk2(s[2 * 33], s[3 * 33]); o.z = pk2(s[4 * 33], s[5 * 33]); o.w = pk2(s[6 * 33], s[7 * 33]);
;         *(v4u*)(WT + (size_t)(prow0 + n) * K + k0 + 8 * c) = o; }
;     asm volatile("s_waitcnt lgkmcnt(0)" ::: "memory");
; __device__ __forceinline__ void weight_copy_items(const Args& a, LAS unsigned char* lds, int lo, int hi, int G) {
;     ...
;         if (r < I4) { const int gi = r >> 3, kb = (r >> 2) & 1, nb = r & 3; transpose_item(a.in[8] + (size_t)gi * 128 * 128, 128, 128, (bf16*)(ws + WS_POOLW) + (size_t)gi * 128 * 128, 32 * nb, 64 * kb, 32 * nb, scr, lane); continue; } r -= I4;
.LBB0_341:
	s_andn2_saveexec_b64 s[18:19], s[42:43]
	s_cbranch_execz .LBB0_343
	v_add_u32_e32 v0, 0xfffffa00, v18
	v_lshrrev_b32_e32 v0, 3, v0
	v_lshlrev_b64 v[12:13], 16, v[0:1]
	v_lshlrev_b64 v[14:15], 15, v[0:1]
	v_add_u32_e32 v0, 0x20600, v27
	v_and_b32_e32 v37, 0x60, v0
	v_and_b32_e32 v11, 64, v29
	v_or_b32_e32 v0, v37, v19
	v_lshl_add_u64 v[12:13], s[52:53], 0, v[12:13]
	v_or_b32_e32 v16, v11, v20
	v_lshlrev_b32_e32 v0, 2, v0
	v_lshl_add_u64 v[12:13], v[12:13], 0, v[0:1]
	v_lshlrev_b32_e32 v0, 9, v16
	v_lshl_add_u64 v[12:13], v[12:13], 0, v[0:1]
	s_movk_i32 s5, 0x1000
	v_add_co_u32_e32 v16, vcc, s5, v12
	s_movk_i32 s5, 0x2000
	s_nop 0
	v_addc_co_u32_e32 v17, vcc, 0, v13, vcc
	v_add_co_u32_e32 v38, vcc, s5, v12
	s_movk_i32 s5, 0x4000
	s_nop 0
	v_addc_co_u32_e32 v39, vcc, 0, v13, vcc
	v_add_co_u32_e32 v40, vcc, s55, v12
	s_nop 1
	v_addc_co_u32_e32 v41, vcc, 0, v13, vcc
	v_add_co_u32_e32 v42, vcc, s5, v12
	s_movk_i32 s5, 0x5000
	s_nop 0
	v_addc_co_u32_e32 v43, vcc, 0, v13, vcc
	global_load_dword v0, v[12:13], off
	global_load_dword v44, v[12:13], off offset:1024
	global_load_dword v45, v[12:13], off offset:2048
	global_load_dword v46, v[12:13], off offset:3072
	global_load_dword v47, v[16:17], off offset:1024
	global_load_dword v48, v[16:17], off offset:2048
	global_load_dword v49, v[16:17], off offset:3072
	global_load_dword v50, v[40:41], off offset:1024
	global_load_dword v51, v[40:41], off offset:2048
	s_nop 0
	global_load_dword v40, v[40:41], off offset:3072
	s_nop 0
	global_load_dword v41, v[38:39], off offset:-4096
	global_load_dword v52, v[38:39], off
	global_load_dword v53, v[38:39], off offset:1024
	global_load_dword v54, v[38:39], off offset:2048
	global_load_dword v55, v[38:39], off offset:3072
	global_load_dword v56, v[42:43], off offset:-4096
	global_load_dword v57, v[42:43], off
	v_add_co_u32_e32 v16, vcc, s5, v12
	s_movk_i32 s5, 0x6000
	s_nop 0
	v_addc_co_u32_e32 v17, vcc, 0, v13, vcc
	v_add_co_u32_e32 v38, vcc, s5, v12
	s_movk_i32 s5, 0x7000
	s_nop 0
	v_addc_co_u32_e32 v39, vcc, 0, v13, vcc
	v_add_co_u32_e32 v12, vcc, s5, v12
	global_load_dword v58, v[42:43], off offset:1024
	global_load_dword v59, v[42:43], off offset:2048
	s_nop 0
	global_load_dword v42, v[42:43], off offset:3072
	s_nop 0
	global_load_dword v43, v[38:39], off offset:-4096
	global_load_dword v60, v[38:39], off
	global_load_dword v61, v[38:39], off offset:1024
	global_load_dword v62, v[38:39], off offset:2048
	s_nop 0
	global_load_dword v38, v[38:39], off offset:3072
	v_addc_co_u32_e32 v13, vcc, 0, v13, vcc
	global_load_dword v39, v[16:17], off offset:1024
	global_load_dword v63, v[16:17], off offset:2048
	s_nop 0
	global_load_dword v16, v[16:17], off offset:3072
	s_nop 0
	global_load_dword v17, v[12:13], off
	global_load_dword v64, v[12:13], off offset:1024
	global_load_dword v65, v[12:13], off offset:2048
	global_load_dword v66, v[12:13], off offset:3072
	v_lshl_add_u64 v[12:13], s[46:47], 0, v[14:15]
	s_waitcnt vmcnt(30)
	ds_write2_b32 v21, v0, v44 offset1:66
	s_waitcnt vmcnt(28)
	ds_write2_b32 v21, v45, v46 offset0:132 offset1:198
	s_waitcnt vmcnt(21)
	ds_write2_b32 v30, v41, v47 offset0:8 offset1:74
	ds_write2_b32 v30, v48, v49 offset0:140 offset1:206
	s_waitcnt vmcnt(19)
	ds_write2_b32 v31, v52, v53 offset0:16 offset1:82
	s_waitcnt vmcnt(17)
	ds_write2_b32 v31, v54, v55 offset0:148 offset1:214
	s_waitcnt vmcnt(16)
	ds_write2_b32 v32, v56, v50 offset0:24 offset1:90
	ds_write2_b32 v32, v51, v40 offset0:156 offset1:222
	s_waitcnt vmcnt(14)
	ds_write2_b32 v33, v57, v58 offset0:32 offset1:98
	s_waitcnt vmcnt(12)
	ds_write2_b32 v33, v59, v42 offset0:164 offset1:230
	s_waitcnt vmcnt(6)
	ds_write2_b32 v34, v43, v39 offset0:40 offset1:106
	s_waitcnt vmcnt(4)
	ds_write2_b32 v34, v63, v16 offset0:172 offset1:238
	ds_write2_b32 v35, v60, v61 offset0:48 offset1:114
	ds_write2_b32 v35, v62, v38 offset0:180 offset1:246
	s_waitcnt vmcnt(2)
	ds_write2_b32 v36, v17, v64 offset0:56 offset1:122
	s_waitcnt vmcnt(0)
	ds_write2_b32 v36, v65, v66 offset0:188 offset1:254
	s_waitcnt lgkmcnt(0)
	ds_read2_b32 v[16:17], v23 offset0:33 offset1:41
	ds_read2_b32 v[38:39], v23 offset1:8
	ds_read2_b32 v[40:41], v23 offset0:66 offset1:74
	ds_read2_b32 v[42:43], v23 offset0:99 offset1:107
	ds_read2_b32 v[44:45], v23 offset0:132 offset1:140
	ds_read2_b32 v[46:47], v23 offset0:165 offset1:173
	ds_read2_b32 v[48:49], v23 offset0:198 offset1:206
	ds_read2_b32 v[50:51], v23 offset0:231 offset1:239
	v_lshlrev_b32_e32 v0, 1, v11
	v_lshl_add_u64 v[12:13], v[12:13], 0, v[0:1]
	v_mov_b32_e32 v11, v1
	v_or_b32_e32 v0, v37, v22
	v_lshl_add_u64 v[52:53], v[12:13], 0, v[10:11]
	v_lshlrev_b32_e32 v0, 8, v0
	s_waitcnt lgkmcnt(6)
	v_cvt_pk_bf16_f32 v12, v38, v16
	s_waitcnt lgkmcnt(4)
	v_cvt_pk_bf16_f32 v13, v40, v42
	s_waitcnt lgkmcnt(2)
	v_cvt_pk_bf16_f32 v14, v44, v46
	s_waitcnt lgkmcnt(0)
	v_cvt_pk_bf16_f32 v15, v48, v50
	v_lshl_add_u64 v[54:55], v[52:53], 0, v[0:1]
	global_store_dwordx4 v[54:55], v[12:15], off sc1
	v_or_b32_e32 v0, v37, v24
	v_lshlrev_b32_e32 v0, 8, v0
	v_cvt_pk_bf16_f32 v12, v39, v17
	v_cvt_pk_bf16_f32 v13, v41, v43
	v_cvt_pk_bf16_f32 v14, v45, v47
	v_cvt_pk_bf16_f32 v15, v49, v51
	ds_read2_b32 v[38:39], v23 offset0:49 offset1:57
	ds_read2_b32 v[40:41], v23 offset0:16 offset1:24
	ds_read2_b32 v[42:43], v23 offset0:82 offset1:90
	ds_read2_b32 v[44:45], v23 offset0:115 offset1:123
	ds_read2_b32 v[46:47], v23 offset0:148 offset1:156
	ds_read2_b32 v[48:49], v23 offset0:181 offset1:189
	ds_read2_b32 v[50:51], v23 offset0:214 offset1:222
	ds_read2_b32 v[54:55], v23 offset0:247 offset1:255
	v_lshl_add_u64 v[16:17], v[52:53], 0, v[0:1]
	v_or_b32_e32 v0, v37, v25
	v_lshlrev_b32_e32 v0, 8, v0
	global_store_dwordx4 v[16:17], v[12:15], off sc1
	v_lshl_add_u64 v[16:17], v[52:53], 0, v[0:1]
	v_or_b32_e32 v0, v37, v26
	s_waitcnt lgkmcnt(6)
	v_cvt_pk_bf16_f32 v12, v40, v38
	s_waitcnt lgkmcnt(4)
	v_cvt_pk_bf16_f32 v13, v42, v44
	s_waitcnt lgkmcnt(2)
	v_cvt_pk_bf16_f32 v14, v46, v48
	s_waitcnt lgkmcnt(0)
	v_cvt_pk_bf16_f32 v15, v50, v54
	v_lshlrev_b32_e32 v0, 8, v0
	global_store_dwordx4 v[16:17], v[12:15], off sc1
	v_lshl_add_u64 v[16:17], v[52:53], 0, v[0:1]
	s_nop 0
	v_cvt_pk_bf16_f32 v12, v41, v39
	v_cvt_pk_bf16_f32 v13, v43, v45
	v_cvt_pk_bf16_f32 v14, v47, v49
	v_cvt_pk_bf16_f32 v15, v51, v55
	global_store_dwordx4 v[16:17], v[12:15], off sc1
	s_waitcnt lgkmcnt(0)

; #define LAS __attribute__((address_space(3)))
; __device__ __forceinline__ void transpose_item(const float* W, int K, int N, bf16* WT, int prow0, int k0, int n0, LAS float* scr, int lane) {
;     float tv[32];
; #pragma unroll
;     for (int i = 0; i < 32; ++i) { const int kk = 2 * i + (lane >> 5), c = n0 + (lane & 31); tv[i] = (c < N) ? W[(size_t)(k0 + kk) * N + c] : 0.f; }
; __device__ __forceinline__ void weight_copy_items(const Args& a, LAS unsigned char* lds, int lo, int hi, int G) {
;     ...
;         if (r < I0) { const int kb = r / 96, nb = r % 96; transpose_item(a.in[6], D, N0, (bf16*)(ws + WS_W0IN), 32 * nb, 64 * kb, 32 * nb, scr, lane); continue; } r -= I0;
.LBB0_344:
	s_andn2_saveexec_b64 s[36:37], s[40:41]
	s_cbranch_execz .LBB0_263
	s_mov_b32 s5, 0x2aaaaaab
	v_mul_hi_i32 v0, v18, s5
	v_lshrrev_b32_e32 v11, 31, v0
	v_ashrrev_i32_e32 v0, 4, v0
	v_add_u32_e32 v0, v0, v11
	s_movk_i32 s5, 0xf400
	v_lshlrev_b32_e32 v12, 6, v0
	v_mul_lo_u32 v0, v0, s5
	v_add_u32_e32 v11, v19, v27
	s_mov_b32 s5, 0x20600
	v_add3_u32 v14, v11, v0, s5
	v_or_b32_e32 v11, v12, v20
	v_ashrrev_i32_e32 v15, 31, v14
	v_lshl_add_u64 v[14:15], v[14:15], 2, s[80:81]
	v_or_b32_e32 v13, 2, v11
	v_mad_i64_i32 v[38:39], s[14:15], v13, s55, v[14:15]
	v_or_b32_e32 v13, 4, v11
	v_mad_i64_i32 v[40:41], s[14:15], v13, s55, v[14:15]
	v_or_b32_e32 v13, 6, v11
	v_mad_i64_i32 v[42:43], s[14:15], v13, s55, v[14:15]
	v_or_b32_e32 v13, 8, v11
	v_mad_i64_i32 v[44:45], s[14:15], v13, s55, v[14:15]
	v_or_b32_e32 v13, 10, v11
	v_mad_i64_i32 v[46:47], s[14:15], v13, s55, v[14:15]
	v_or_b32_e32 v13, 12, v11
	v_mad_i64_i32 v[48:49], s[14:15], v13, s55, v[14:15]
	v_or_b32_e32 v13, 14, v11
	v_mad_i64_i32 v[16:17], s[14:15], v11, s55, v[14:15]
	v_mad_i64_i32 v[50:51], s[14:15], v13, s55, v[14:15]
	global_load_dword v13, v[16:17], off
	global_load_dword v37, v[38:39], off
	global_load_dword v52, v[40:41], off
	global_load_dword v53, v[42:43], off
	global_load_dword v54, v[44:45], off
	global_load_dword v55, v[46:47], off
	global_load_dword v56, v[48:49], off
	global_load_dword v57, v[50:51], off
	v_or_b32_e32 v16, 16, v11
	v_or_b32_e32 v38, 18, v11
	v_or_b32_e32 v40, 20, v11
	v_or_b32_e32 v42, 22, v11
	v_or_b32_e32 v44, 24, v11
	v_or_b32_e32 v46, 26, v11
	v_or_b32_e32 v48, 28, v11
	v_or_b32_e32 v50, 30, v11
	v_mad_i64_i32 v[16:17], s[14:15], v16, s55, v[14:15]
	v_mad_i64_i32 v[38:39], s[14:15], v38, s55, v[14:15]
	v_mad_i64_i32 v[40:41], s[14:15], v40, s55, v[14:15]
	v_mad_i64_i32 v[42:43], s[14:15], v42, s55, v[14:15]
	v_mad_i64_i32 v[44:45], s[14:15], v44, s55, v[14:15]
	v_mad_i64_i32 v[46:47], s[14:15], v46, s55, v[14:15]
	v_mad_i64_i32 v[48:49], s[14:15], v48, s55, v[14:15]
	v_mad_i64_i32 v[50:51], s[14:15], v50, s55, v[14:15]
	global_load_dword v58, v[16:17], off
	global_load_dword v59, v[38:39], off
	global_load_dword v60, v[40:41], off
	global_load_dword v61, v[42:43], off
	global_load_dword v62, v[44:45], off
	global_load_dword v63, v[46:47], off
	global_load_dword v64, v[48:49], off
	global_load_dword v65, v[50:51], off
	v_or_b32_e32 v16, 32, v11
	v_or_b32_e32 v38, 34, v11
	v_or_b32_e32 v40, 36, v11
	v_or_b32_e32 v42, 38, v11
	v_or_b32_e32 v44, 40, v11
	v_or_b32_e32 v46, 42, v11
	v_or_b32_e32 v48, 44, v11
	v_or_b32_e32 v50, 46, v11
	v_mad_i64_i32 v[16:17], s[14:15], v16, s55, v[14:15]
	v_mad_i64_i32 v[38:39], s[14:15], v38, s55, v[14:15]
	v_mad_i64_i32 v[40:41], s[14:15], v40, s55, v[14:15]
	v_mad_i64_i32 v[42:43], s[14:15], v42, s55, v[14:15]
	v_mad_i64_i32 v[44:45], s[14:15], v44, s55, v[14:15]
	v_mad_i64_i32 v[46:47], s[14:15], v46, s55, v[14:15]
	v_mad_i64_i32 v[48:49], s[14:15], v48, s55, v[14:15]
	v_mad_i64_i32 v[50:51], s[14:15], v50, s55, v[14:15]
	global_load_dword v66, v[16:17], off
	global_load_dword v67, v[38:39], off
	global_load_dword v68, v[40:41], off
	global_load_dword v69, v[42:43], off
	global_load_dword v70, v[44:45], off
	global_load_dword v71, v[46:47], off
	global_load_dword v72, v[48:49], off
	s_nop 0
	global_load_dword v50, v[50:51], off
	v_or_b32_e32 v16, 48, v11
	v_or_b32_e32 v38, 50, v11
	v_or_b32_e32 v40, 52, v11
	v_or_b32_e32 v42, 54, v11
	v_or_b32_e32 v44, 56, v11
	v_or_b32_e32 v46, 58, v11
	v_or_b32_e32 v48, 60, v11
	v_or_b32_e32 v11, 62, v11
	v_mad_i64_i32 v[16:17], s[14:15], v16, s55, v[14:15]
	v_mad_i64_i32 v[38:39], s[14:15], v38, s55, v[14:15]
	v_mad_i64_i32 v[40:41], s[14:15], v40, s55, v[14:15]
	v_mad_i64_i32 v[42:43], s[14:15], v42, s55, v[14:15]
	v_mad_i64_i32 v[44:45], s[14:15], v44, s55, v[14:15]
	v_mad_i64_i32 v[46:47], s[14:15], v46, s55, v[14:15]
	v_mad_i64_i32 v[48:49], s[14:15], v48, s55, v[14:15]
	v_mad_i64_i32 v[14:15], s[14:15], v11, s55, v[14:15]
	global_load_dword v11, v[16:17], off
	s_nop 0
	global_load_dword v16, v[38:39], off
	global_load_dword v17, v[40:41], off
	s_nop 0
	global_load_dword v38, v[42:43], off
	global_load_dword v39, v[44:45], off
	global_load_dword v40, v[46:47], off
	global_load_dword v41, v[48:49], off
	s_nop 0
	global_load_dword v14, v[14:15], off
	s_waitcnt vmcnt(30)
; #define LAS __attribute__((address_space(3)))
; __device__ __forceinline__ unsigned pk2(float lo, float hi) { f32x2_t v = {lo, hi}; bf16x2_t b = __builtin_convertvector(v, bf16x2_t); return __builtin_bit_cast(unsigned, b); }
; __device__ __forceinline__ void transpose_item(const float* W, int K, int N, bf16* WT, int prow0, int k0, int n0, LAS float* scr, int lane) {
;     ...
;     for (int i = 0; i < 32; ++i) { const int kk = 2 * i + (lane >> 5); scr[kk * 33 + (lane & 31)] = tv[i]; }
;     asm volatile("s_waitcnt lgkmcnt(0)" ::: "memory");
;     const int c = lane & 7;
; #pragma unroll
;     for (int j = 0; j < 4; ++j) { const int n = (lane >> 3) + 8 * j; const LAS float* s = scr + (8 * c) * 33 + n;
;         v4u o; o.x = pk2(s[0 * 33], s[1 * 33]); o.y = pk2(s[2 * 33], s[3 * 33]); o.z = pk2(s[4 * 33], s[5 * 33]); o.w = pk2(s[6 * 33], s[7 * 33]);
;         *(v4u*)(WT + (size_t)(prow0 + n) * K + k0 + 8 * c) = o; }
;     asm volatile("s_waitcnt lgkmcnt(0)" ::: "memory");
	ds_write2_b32 v21, v13, v37 offset1:66
	s_waitcnt vmcnt(28)
	ds_write2_b32 v21, v52, v53 offset0:132 offset1:198
	s_waitcnt vmcnt(26)
	ds_write2_b32 v30, v54, v55 offset0:8 offset1:74
	s_waitcnt vmcnt(24)
	ds_write2_b32 v30, v56, v57 offset0:140 offset1:206
	s_waitcnt vmcnt(22)
	ds_write2_b32 v31, v58, v59 offset0:16 offset1:82
	s_waitcnt vmcnt(20)
	ds_write2_b32 v31, v60, v61 offset0:148 offset1:214
	s_waitcnt vmcnt(18)
	ds_write2_b32 v32, v62, v63 offset0:24 offset1:90
	s_waitcnt vmcnt(16)
	ds_write2_b32 v32, v64, v65 offset0:156 offset1:222
	s_waitcnt vmcnt(14)
	ds_write2_b32 v33, v66, v67 offset0:32 offset1:98
	s_waitcnt vmcnt(12)
	ds_write2_b32 v33, v68, v69 offset0:164 offset1:230
	s_waitcnt vmcnt(10)
	ds_write2_b32 v34, v70, v71 offset0:40 offset1:106
	s_waitcnt vmcnt(8)
	ds_write2_b32 v34, v72, v50 offset0:172 offset1:238
	s_waitcnt vmcnt(6)
	ds_write2_b32 v35, v11, v16 offset0:48 offset1:114
	s_waitcnt vmcnt(4)
	ds_write2_b32 v35, v17, v38 offset0:180 offset1:246
	s_waitcnt vmcnt(2)
	ds_write2_b32 v36, v39, v40 offset0:56 offset1:122
	s_waitcnt vmcnt(0)
	ds_write2_b32 v36, v41, v14 offset0:188 offset1:254
	s_waitcnt lgkmcnt(0)
	ds_read2_b32 v[16:17], v23 offset0:33 offset1:41
	ds_read2_b32 v[38:39], v23 offset1:8
	ds_read2_b32 v[40:41], v23 offset0:66 offset1:74
	ds_read2_b32 v[42:43], v23 offset0:99 offset1:107
	ds_read2_b32 v[44:45], v23 offset0:132 offset1:140
	ds_read2_b32 v[46:47], v23 offset0:165 offset1:173
	ds_read2_b32 v[48:49], v23 offset0:198 offset1:206
	ds_read2_b32 v[50:51], v23 offset0:231 offset1:239
	v_add3_u32 v0, v22, v27, v0
	v_add_u32_e32 v54, 0x20600, v0
	v_ashrrev_i32_e32 v13, 31, v12
	v_ashrrev_i32_e32 v55, 31, v54
	v_lshl_add_u64 v[52:53], v[12:13], 1, v[8:9]
	v_lshlrev_b64 v[54:55], 11, v[54:55]
	s_waitcnt lgkmcnt(6)
	v_cvt_pk_bf16_f32 v12, v38, v16
	s_waitcnt lgkmcnt(4)
	v_cvt_pk_bf16_f32 v13, v40, v42
	s_waitcnt lgkmcnt(2)
	v_cvt_pk_bf16_f32 v14, v44, v46
	s_waitcnt lgkmcnt(0)
	v_cvt_pk_bf16_f32 v15, v48, v50
	v_lshl_add_u64 v[54:55], v[52:53], 0, v[54:55]
	v_add_u32_e32 v16, 0x20608, v0
	global_store_dwordx4 v[54:55], v[12:15], off sc1
	s_nop 1
	v_cvt_pk_bf16_f32 v12, v39, v17
	v_ashrrev_i32_e32 v17, 31, v16
	v_cvt_pk_bf16_f32 v13, v41, v43
	v_cvt_pk_bf16_f32 v14, v45, v47
	v_cvt_pk_bf16_f32 v15, v49, v51
	v_lshlrev_b64 v[16:17], 11, v[16:17]
	ds_read2_b32 v[38:39], v23 offset0:49 offset1:57
	ds_read2_b32 v[40:41], v23 offset0:16 offset1:24
	ds_read2_b32 v[42:43], v23 offset0:82 offset1:90
	ds_read2_b32 v[44:45], v23 offset0:115 offset1:123
	ds_read2_b32 v[46:47], v23 offset0:148 offset1:156
	ds_read2_b32 v[48:49], v23 offset0:181 offset1:189
	ds_read2_b32 v[50:51], v23 offset0:214 offset1:222
	ds_read2_b32 v[54:55], v23 offset0:247 offset1:255
	v_lshl_add_u64 v[16:17], v[52:53], 0, v[16:17]
	global_store_dwordx4 v[16:17], v[12:15], off sc1
	v_add_u32_e32 v16, 0x20610, v0
	v_ashrrev_i32_e32 v17, 31, v16
	v_lshlrev_b64 v[16:17], 11, v[16:17]
	s_waitcnt lgkmcnt(6)
	v_cvt_pk_bf16_f32 v12, v40, v38
	s_waitcnt lgkmcnt(4)
	v_cvt_pk_bf16_f32 v13, v42, v44
	s_waitcnt lgkmcnt(2)
	v_cvt_pk_bf16_f32 v14, v46, v48
	s_waitcnt lgkmcnt(0)
	v_cvt_pk_bf16_f32 v15, v50, v54
	v_lshl_add_u64 v[16:17], v[52:53], 0, v[16:17]
	global_store_dwordx4 v[16:17], v[12:15], off sc1
	v_add_u32_e32 v16, 0x20618, v0
	v_ashrrev_i32_e32 v17, 31, v16
	v_lshlrev_b64 v[16:17], 11, v[16:17]
	v_cvt_pk_bf16_f32 v12, v41, v39
	v_cvt_pk_bf16_f32 v13, v43, v45
	v_cvt_pk_bf16_f32 v14, v47, v49
	v_cvt_pk_bf16_f32 v15, v51, v55
	v_lshl_add_u64 v[16:17], v[52:53], 0, v[16:17]
	global_store_dwordx4 v[16:17], v[12:15], off sc1
	s_waitcnt lgkmcnt(0)
	s_branch .LBB0_263

; #define GSYNC() do { xcd_barrier(xbar); xcd_barrier(xbar); } while (0)
; #define GSYNC() xcd_barrier(xbar)
; #define REP(p) for (int rep_ = 0; rep_ < (((PROBE_MASK >> (p)) & 1) ? 2 : 1); ++rep_)
; __device__ __forceinline__ void hgrn_scan_phase(const float* __restrict__ Lst, const float* __restrict__ Dtot, float* __restrict__ Sst, int G) {
;     ...
;     for (int e = blockIdx.x * NTHR + tid; e < 8 * 16384; e += G * NTHR) {
;         const int bh = e >> 14, kv = e & 16383, kk = kv >> 7;
;         float s = 0.f;
; #pragma unroll 8
;         for (int sc = 0; sc < 32; ++sc) { const size_t u = (size_t)(bh * 32 + sc);
;             Sst[u * 16384 + kv] = s;
;             s = Dtot[u * 128 + kk] * s + Lst[u * 16384 + kv]; }
;     }
; __global__ void __launch_bounds__(NTHR, 2) fwd_megakernel(Args args) {
;     ...
;     REP(4) { hgrn_scan_phase((const float*)(ws + WS_LST), (const float*)(ws + WS_DTOT), (float*)(ws + WS_SST), G);
;     GSYNC(); }
;     REP(5) { for (int u = blockIdx.x; u < 256; u += G) hgrn_unit<true>(lds, u, P0, args.in[5], args.in[7], nullptr, (const float*)(ws + WS_SST), nullptr, MIX);
.LBB0_401:
	v_lshl_add_u64 v[4:5], s[10:11], 0, v[2:3]
	v_lshl_add_u64 v[6:7], s[10:11], 0, v[0:1]
	v_add_co_u32_e32 v14, vcc, 0xc800000, v4
	s_mov_b64 s[36:37], vcc
	v_add_co_u32_e32 v8, vcc, 0xd800000, v6
	s_mov_b64 s[14:15], 0x1000
	s_nop 0
	v_addc_co_u32_e32 v9, vcc, 0, v7, vcc
	v_add_co_u32_e32 v6, vcc, 0xb800000, v4
	global_load_dword v13, v[8:9], off
	s_nop 0
	v_addc_co_u32_e32 v7, vcc, 0, v5, vcc
	global_load_dword v26, v[6:7], off
	v_addc_co_u32_e64 v15, vcc, 0, v5, s[36:37]
	global_store_dword v[14:15], v12, off sc1
	v_add_co_u32_e32 v6, vcc, 0xc810000, v4
	global_load_dword v27, v[8:9], off offset:512
	global_load_dword v28, v[8:9], off offset:1024
	global_load_dword v29, v[8:9], off offset:1536
	global_load_dword v30, v[8:9], off offset:2048
	global_load_dword v31, v[8:9], off offset:2560
	global_load_dword v32, v[8:9], off offset:3072
	global_load_dword v33, v[8:9], off offset:3584
	s_mov_b64 s[36:37], vcc
	v_add_co_u32_e32 v8, vcc, 0xb810000, v4
	s_add_i32 s16, s16, -8
	s_nop 0
	v_addc_co_u32_e32 v9, vcc, 0, v5, vcc
	v_add_co_u32_e32 v14, vcc, 0xc820000, v4
	global_load_dword v34, v[8:9], off
	s_mov_b64 s[38:39], vcc
	v_add_co_u32_e32 v8, vcc, 0xb820000, v4
	v_lshl_add_u64 v[0:1], v[0:1], 0, s[14:15]
	s_nop 0
	v_addc_co_u32_e32 v9, vcc, 0, v5, vcc
	v_add_co_u32_e32 v16, vcc, 0xc830000, v4
	global_load_dword v35, v[8:9], off
	s_mov_b64 s[40:41], vcc
	v_add_co_u32_e32 v8, vcc, 0xb830000, v4
	v_lshl_add_u64 v[2:3], v[2:3], 0, s[18:19]
	s_nop 0
	v_addc_co_u32_e32 v9, vcc, 0, v5, vcc
	v_add_co_u32_e32 v18, vcc, 0xc840000, v4
	global_load_dword v36, v[8:9], off
	s_mov_b64 s[42:43], vcc
	v_add_co_u32_e32 v8, vcc, 0xb840000, v4
	s_cmp_eq_u32 s16, 0
	s_nop 0
	v_addc_co_u32_e32 v9, vcc, 0, v5, vcc
	v_add_co_u32_e32 v20, vcc, 0xc850000, v4
	global_load_dword v37, v[8:9], off
	s_mov_b64 s[44:45], vcc
	v_add_co_u32_e32 v8, vcc, 0xb850000, v4
	s_waitcnt vmcnt(12)
	v_fmac_f32_e32 v26, v12, v13
	v_addc_co_u32_e32 v9, vcc, 0, v5, vcc
	v_add_co_u32_e32 v22, vcc, 0xc860000, v4
	global_load_dword v38, v[8:9], off
	s_mov_b64 s[46:47], vcc
	v_add_co_u32_e32 v8, vcc, 0xb860000, v4
	s_waitcnt vmcnt(4)
	v_fmac_f32_e32 v34, v26, v27
	v_addc_co_u32_e32 v9, vcc, 0, v5, vcc
	v_add_co_u32_e32 v24, vcc, 0xc870000, v4
	global_load_dword v39, v[8:9], off
	s_mov_b64 s[48:49], vcc
	v_add_co_u32_e32 v8, vcc, 0xb870000, v4
	s_waitcnt vmcnt(4)
	v_fmac_f32_e32 v35, v34, v28
	v_addc_co_u32_e32 v9, vcc, 0, v5, vcc
	global_load_dword v12, v[8:9], off
	v_addc_co_u32_e64 v7, vcc, 0, v5, s[36:37]
	v_addc_co_u32_e64 v15, vcc, 0, v5, s[38:39]
	v_addc_co_u32_e64 v17, vcc, 0, v5, s[40:41]
	s_waitcnt vmcnt(4)
	v_fmac_f32_e32 v36, v35, v29
	v_addc_co_u32_e64 v19, vcc, 0, v5, s[42:43]
	v_addc_co_u32_e64 v21, vcc, 0, v5, s[44:45]
	v_addc_co_u32_e64 v23, vcc, 0, v5, s[46:47]
	v_addc_co_u32_e64 v25, vcc, 0, v5, s[48:49]
	s_waitcnt vmcnt(3)
	v_fmac_f32_e32 v37, v36, v30
	global_store_dword v[6:7], v26, off sc1
	global_store_dword v[14:15], v34, off sc1
	global_store_dword v[16:17], v35, off sc1
	global_store_dword v[18:19], v36, off sc1
	global_store_dword v[20:21], v37, off sc1
	s_waitcnt vmcnt(7)
	v_fmac_f32_e32 v38, v37, v31
	global_store_dword v[22:23], v38, off sc1
	s_waitcnt vmcnt(7)
	v_fmac_f32_e32 v39, v38, v32
	global_store_dword v[24:25], v39, off sc1
	s_waitcnt vmcnt(7)
	v_fmac_f32_e32 v12, v39, v33
	s_cbranch_scc0 .LBB0_401
	v_add_u32_e32 v10, s5, v10
	s_mov_b32 s14, 0x1ffff
	v_cmp_lt_i32_e32 vcc, s14, v10
	s_or_b64 s[50:51], vcc, s[50:51]
	v_add_u16_e32 v11, s5, v11
	s_andn2_b64 exec, exec, s[50:51]
	s_cbranch_execnz .LBB0_400
.LBB0_403:
	s_or_b64 exec, exec, s[0:1]
	s_waitcnt vmcnt(0)
	s_barrier
	s_cmp_eq_u32 s6, 0x100
	s_cbranch_scc0 .Lg5_orig
	s_and_saveexec_b64 s[0:1], s[92:93]
	s_cbranch_execz .Lg5_done
	v_readlane_b32 s98, v249, 2
	s_lshr_b32 s98, s98, 5
	s_lshl_b32 s98, s98, 8
	s_add_i32 s98, s98, 0x1000
	v_mov_b32_e32 v250, s98
	v_mov_b32_e32 v251, 1
	global_atomic_add v250, v251, s[10:11]
.Lg5_poll:
	global_load_dword v251, v250, s[10:11] sc1
	s_waitcnt vmcnt(0)
	v_cmp_gt_u32_e32 vcc, 32, v251
	s_nop 1
	s_cbranch_vccz .Lg5_pollend
	s_sleep 1
	s_branch .Lg5_poll

; __device__ __forceinline__ void xcd_barrier(const XcdBarrier& b) {
;     asm volatile("s_waitcnt vmcnt(0)" ::: "memory");
;     __syncthreads();
;     if (threadIdx.x == 0) {
;         unsigned* bar = b.bar;
;         __builtin_amdgcn_s_waitcnt(0);
;         unsigned nloc = b.st[0], nx = b.st[1];
;         if (nloc == 0u) { xcd_barrier_complete(bar, b.x, nloc, nx); b.st[0] = nloc; b.st[1] = nx; }
.Lg5_done:
	s_branch .LBB0_455
.Lg5_orig:
	s_and_saveexec_b64 s[0:1], s[92:93]
	v_readlane_b32 s16, v249, 5
	v_readlane_b32 s17, v249, 6
	s_cbranch_execz .LBB0_455
	s_add_i32 s5, 0, 0x23fc0
	v_mov_b32_e32 v0, s5
	s_waitcnt vmcnt(0) expcnt(0) lgkmcnt(0)
	ds_read_b32 v2, v0
	s_add_i32 s5, 0, 0x23fc4
	v_mov_b32_e32 v0, s5
	ds_read_b32 v0, v0
	s_waitcnt lgkmcnt(1)
	v_cmp_ne_u32_e32 vcc, 0, v2
	s_cbranch_vccnz .LBB0_419
	s_mov_b32 s5, 1
	v_mov_b32_e32 v16, 0
	s_branch .LBB0_407
